# P3 retention scan: 32 chunk loads per pass issued up front with a counted vmcnt(32) chain instead of a full drain every 8 steps
# speedup vs baseline: 1.0033x; 1.0033x over previous
.LBB0_636:
	v_lshl_add_u64 v[14:15], s[22:23], 0, v[6:7]
	v_lshl_add_u64 v[16:17], s[22:23], 0, v[4:5]
	s_mov_b64 s[38:39], 0x15ba4000
	s_mov_b64 s[40:41], 0x17ba4000
	v_lshl_add_u64 v[16:17], v[16:17], 0, s[38:39]
	v_lshl_add_u64 v[14:15], v[14:15], 0, s[40:41]
	s_mov_b64 s[38:39], 0x4000
	s_mov_b64 s[40:41], 0x2000
	global_load_dword v40, v[16:17], off nt
	v_lshl_add_u64 v[16:17], v[16:17], 0, s[38:39]
	global_load_dword v41, v[16:17], off nt
	v_lshl_add_u64 v[16:17], v[16:17], 0, s[38:39]
	global_load_dword v42, v[16:17], off nt
	v_lshl_add_u64 v[16:17], v[16:17], 0, s[38:39]
	global_load_dword v43, v[16:17], off nt
	v_lshl_add_u64 v[16:17], v[16:17], 0, s[38:39]
	global_load_dword v44, v[16:17], off nt
	v_lshl_add_u64 v[16:17], v[16:17], 0, s[38:39]
	global_load_dword v45, v[16:17], off nt
	v_lshl_add_u64 v[16:17], v[16:17], 0, s[38:39]
	global_load_dword v46, v[16:17], off nt
	v_lshl_add_u64 v[16:17], v[16:17], 0, s[38:39]
	global_load_dword v47, v[16:17], off nt
	v_lshl_add_u64 v[16:17], v[16:17], 0, s[38:39]
	global_load_dword v48, v[16:17], off nt
	v_lshl_add_u64 v[16:17], v[16:17], 0, s[38:39]
	global_load_dword v49, v[16:17], off nt
	v_lshl_add_u64 v[16:17], v[16:17], 0, s[38:39]
	global_load_dword v50, v[16:17], off nt
	v_lshl_add_u64 v[16:17], v[16:17], 0, s[38:39]
	global_load_dword v51, v[16:17], off nt
	v_lshl_add_u64 v[16:17], v[16:17], 0, s[38:39]
	global_load_dword v52, v[16:17], off nt
	v_lshl_add_u64 v[16:17], v[16:17], 0, s[38:39]
	global_load_dword v53, v[16:17], off nt
	v_lshl_add_u64 v[16:17], v[16:17], 0, s[38:39]
	global_load_dword v54, v[16:17], off nt
	v_lshl_add_u64 v[16:17], v[16:17], 0, s[38:39]
	global_load_dword v55, v[16:17], off nt
	v_lshl_add_u64 v[16:17], v[16:17], 0, s[38:39]
	global_load_dword v56, v[16:17], off nt
	v_lshl_add_u64 v[16:17], v[16:17], 0, s[38:39]
	global_load_dword v57, v[16:17], off nt
	v_lshl_add_u64 v[16:17], v[16:17], 0, s[38:39]
	global_load_dword v58, v[16:17], off nt
	v_lshl_add_u64 v[16:17], v[16:17], 0, s[38:39]
	global_load_dword v59, v[16:17], off nt
	v_lshl_add_u64 v[16:17], v[16:17], 0, s[38:39]
	global_load_dword v60, v[16:17], off nt
	v_lshl_add_u64 v[16:17], v[16:17], 0, s[38:39]
	global_load_dword v61, v[16:17], off nt
	v_lshl_add_u64 v[16:17], v[16:17], 0, s[38:39]
	global_load_dword v62, v[16:17], off nt
	v_lshl_add_u64 v[16:17], v[16:17], 0, s[38:39]
	global_load_dword v63, v[16:17], off nt
	v_lshl_add_u64 v[16:17], v[16:17], 0, s[38:39]
	global_load_dword v64, v[16:17], off nt
	v_lshl_add_u64 v[16:17], v[16:17], 0, s[38:39]
	global_load_dword v65, v[16:17], off nt
	v_lshl_add_u64 v[16:17], v[16:17], 0, s[38:39]
	global_load_dword v66, v[16:17], off nt
	v_lshl_add_u64 v[16:17], v[16:17], 0, s[38:39]
	global_load_dword v67, v[16:17], off nt
	v_lshl_add_u64 v[16:17], v[16:17], 0, s[38:39]
	global_load_dword v68, v[16:17], off nt
	v_lshl_add_u64 v[16:17], v[16:17], 0, s[38:39]
	global_load_dword v69, v[16:17], off nt
	v_lshl_add_u64 v[16:17], v[16:17], 0, s[38:39]
	global_load_dword v70, v[16:17], off nt
	v_lshl_add_u64 v[16:17], v[16:17], 0, s[38:39]
	global_load_dword v71, v[16:17], off nt
	s_waitcnt lgkmcnt(0)
	v_cvt_pk_bf16_f32 v13, v12, s0
	global_store_short v[14:15], v13, off
	v_lshl_add_u64 v[14:15], v[14:15], 0, s[40:41]
	s_waitcnt vmcnt(32)
	v_fmac_f32_e32 v40, v0, v12
	v_cvt_pk_bf16_f32 v13, v40, s0
	global_store_short v[14:15], v13, off
	v_lshl_add_u64 v[14:15], v[14:15], 0, s[40:41]
	s_waitcnt vmcnt(32)
	v_fmac_f32_e32 v41, v0, v40
	v_cvt_pk_bf16_f32 v13, v41, s0
	global_store_short v[14:15], v13, off
	v_lshl_add_u64 v[14:15], v[14:15], 0, s[40:41]
	s_waitcnt vmcnt(32)
	v_fmac_f32_e32 v42, v0, v41
	v_cvt_pk_bf16_f32 v13, v42, s0
	global_store_short v[14:15], v13, off
	v_lshl_add_u64 v[14:15], v[14:15], 0, s[40:41]
	s_waitcnt vmcnt(32)
	v_fmac_f32_e32 v43, v0, v42
	v_cvt_pk_bf16_f32 v13, v43, s0
	global_store_short v[14:15], v13, off
	v_lshl_add_u64 v[14:15], v[14:15], 0, s[40:41]
	s_waitcnt vmcnt(32)
	v_fmac_f32_e32 v44, v0, v43
	v_cvt_pk_bf16_f32 v13, v44, s0
	global_store_short v[14:15], v13, off
	v_lshl_add_u64 v[14:15], v[14:15], 0, s[40:41]
	s_waitcnt vmcnt(32)
	v_fmac_f32_e32 v45, v0, v44
	v_cvt_pk_bf16_f32 v13, v45, s0
	global_store_short v[14:15], v13, off
	v_lshl_add_u64 v[14:15], v[14:15], 0, s[40:41]
	s_waitcnt vmcnt(32)
	v_fmac_f32_e32 v46, v0, v45
	v_cvt_pk_bf16_f32 v13, v46, s0
	global_store_short v[14:15], v13, off
	v_lshl_add_u64 v[14:15], v[14:15], 0, s[40:41]
	s_waitcnt vmcnt(32)
	v_fmac_f32_e32 v47, v0, v46
	v_cvt_pk_bf16_f32 v13, v47, s0
	global_store_short v[14:15], v13, off
	v_lshl_add_u64 v[14:15], v[14:15], 0, s[40:41]
	s_waitcnt vmcnt(32)
	v_fmac_f32_e32 v48, v0, v47
	v_cvt_pk_bf16_f32 v13, v48, s0
	global_store_short v[14:15], v13, off
	v_lshl_add_u64 v[14:15], v[14:15], 0, s[40:41]
	s_waitcnt vmcnt(32)
	v_fmac_f32_e32 v49, v0, v48
	v_cvt_pk_bf16_f32 v13, v49, s0
	global_store_short v[14:15], v13, off
	v_lshl_add_u64 v[14:15], v[14:15], 0, s[40:41]
	s_waitcnt vmcnt(32)
	v_fmac_f32_e32 v50, v0, v49
	v_cvt_pk_bf16_f32 v13, v50, s0
	global_store_short v[14:15], v13, off
	v_lshl_add_u64 v[14:15], v[14:15], 0, s[40:41]
	s_waitcnt vmcnt(32)
	v_fmac_f32_e32 v51, v0, v50
	v_cvt_pk_bf16_f32 v13, v51, s0
	global_store_short v[14:15], v13, off
	v_lshl_add_u64 v[14:15], v[14:15], 0, s[40:41]
	s_waitcnt vmcnt(32)
	v_fmac_f32_e32 v52, v0, v51
	v_cvt_pk_bf16_f32 v13, v52, s0
	global_store_short v[14:15], v13, off
	v_lshl_add_u64 v[14:15], v[14:15], 0, s[40:41]
	s_waitcnt vmcnt(32)
	v_fmac_f32_e32 v53, v0, v52
	v_cvt_pk_bf16_f32 v13, v53, s0
	global_store_short v[14:15], v13, off
	v_lshl_add_u64 v[14:15], v[14:15], 0, s[40:41]
	s_waitcnt vmcnt(32)
	v_fmac_f32_e32 v54, v0, v53
	v_cvt_pk_bf16_f32 v13, v54, s0
	global_store_short v[14:15], v13, off
	v_lshl_add_u64 v[14:15], v[14:15], 0, s[40:41]
	s_waitcnt vmcnt(32)
	v_fmac_f32_e32 v55, v0, v54
	v_cvt_pk_bf16_f32 v13, v55, s0
	global_store_short v[14:15], v13, off
	v_lshl_add_u64 v[14:15], v[14:15], 0, s[40:41]
	s_waitcnt vmcnt(32)
	v_fmac_f32_e32 v56, v0, v55
	v_cvt_pk_bf16_f32 v13, v56, s0
	global_store_short v[14:15], v13, off
	v_lshl_add_u64 v[14:15], v[14:15], 0, s[40:41]
	s_waitcnt vmcnt(32)
	v_fmac_f32_e32 v57, v0, v56
	v_cvt_pk_bf16_f32 v13, v57, s0
	global_store_short v[14:15], v13, off
	v_lshl_add_u64 v[14:15], v[14:15], 0, s[40:41]
	s_waitcnt vmcnt(32)
	v_fmac_f32_e32 v58, v0, v57
	v_cvt_pk_bf16_f32 v13, v58, s0
	global_store_short v[14:15], v13, off
	v_lshl_add_u64 v[14:15], v[14:15], 0, s[40:41]
	s_waitcnt vmcnt(32)
	v_fmac_f32_e32 v59, v0, v58
	v_cvt_pk_bf16_f32 v13, v59, s0
	global_store_short v[14:15], v13, off
	v_lshl_add_u64 v[14:15], v[14:15], 0, s[40:41]
	s_waitcnt vmcnt(32)
	v_fmac_f32_e32 v60, v0, v59
	v_cvt_pk_bf16_f32 v13, v60, s0
	global_store_short v[14:15], v13, off
	v_lshl_add_u64 v[14:15], v[14:15], 0, s[40:41]
	s_waitcnt vmcnt(32)
	v_fmac_f32_e32 v61, v0, v60
	v_cvt_pk_bf16_f32 v13, v61, s0
	global_store_short v[14:15], v13, off
	v_lshl_add_u64 v[14:15], v[14:15], 0, s[40:41]
	s_waitcnt vmcnt(32)
	v_fmac_f32_e32 v62, v0, v61
	v_cvt_pk_bf16_f32 v13, v62, s0
	global_store_short v[14:15], v13, off
	v_lshl_add_u64 v[14:15], v[14:15], 0, s[40:41]
	s_waitcnt vmcnt(32)
	v_fmac_f32_e32 v63, v0, v62
	v_cvt_pk_bf16_f32 v13, v63, s0
	global_store_short v[14:15], v13, off
	v_lshl_add_u64 v[14:15], v[14:15], 0, s[40:41]
	s_waitcnt vmcnt(32)
	v_fmac_f32_e32 v64, v0, v63
	v_cvt_pk_bf16_f32 v13, v64, s0
	global_store_short v[14:15], v13, off
	v_lshl_add_u64 v[14:15], v[14:15], 0, s[40:41]
	s_waitcnt vmcnt(32)
	v_fmac_f32_e32 v65, v0, v64
	v_cvt_pk_bf16_f32 v13, v65, s0
	global_store_short v[14:15], v13, off
	v_lshl_add_u64 v[14:15], v[14:15], 0, s[40:41]
	s_waitcnt vmcnt(32)
	v_fmac_f32_e32 v66, v0, v65
	v_cvt_pk_bf16_f32 v13, v66, s0
	global_store_short v[14:15], v13, off
	v_lshl_add_u64 v[14:15], v[14:15], 0, s[40:41]
	s_waitcnt vmcnt(32)
	v_fmac_f32_e32 v67, v0, v66
	v_cvt_pk_bf16_f32 v13, v67, s0
	global_store_short v[14:15], v13, off
	v_lshl_add_u64 v[14:15], v[14:15], 0, s[40:41]
	s_waitcnt vmcnt(32)
	v_fmac_f32_e32 v68, v0, v67
	v_cvt_pk_bf16_f32 v13, v68, s0
	global_store_short v[14:15], v13, off
	v_lshl_add_u64 v[14:15], v[14:15], 0, s[40:41]
	s_waitcnt vmcnt(32)
	v_fmac_f32_e32 v69, v0, v68
	v_cvt_pk_bf16_f32 v13, v69, s0
	global_store_short v[14:15], v13, off
	v_lshl_add_u64 v[14:15], v[14:15], 0, s[40:41]
	s_waitcnt vmcnt(32)
	v_fmac_f32_e32 v70, v0, v69
	v_cvt_pk_bf16_f32 v13, v70, s0
	global_store_short v[14:15], v13, off
	v_lshl_add_u64 v[14:15], v[14:15], 0, s[40:41]
	s_waitcnt vmcnt(32)
	v_fmac_f32_e32 v71, v0, v70
	v_mov_b32_e32 v12, v71
	v_ashrrev_i32_e32 v3, 31, v2
	v_lshlrev_b64 v[2:3], 14, v[2:3]
	v_lshlrev_b32_e32 v0, 8, v8
	v_and_b32_e32 v4, 0xfc0, v8
	v_lshl_add_u64 v[2:3], s[20:21], 0, v[2:3]
	v_and_b32_e32 v0, 0x3f00, v0
	v_lshl_add_u64 v[2:3], v[2:3], 0, v[0:1]
	v_lshrrev_b32_e32 v0, 4, v4
	v_lshl_add_u64 v[2:3], v[2:3], 0, v[0:1]
	v_add_co_u32_e32 v2, vcc, 0x8500000, v2
	v_add_u32_e32 v8, s33, v8
	s_nop 0
	v_addc_co_u32_e32 v3, vcc, 0, v3, vcc
	v_cmp_lt_i32_e32 vcc, s35, v8
	s_or_b64 s[26:27], vcc, s[26:27]
	v_add_u16_e32 v9, s33, v9
	global_store_dword v[2:3], v12, off
	s_andn2_b64 exec, exec, s[26:27]
	s_cbranch_execnz .LBB0_635
